# speedup vs baseline: 1.0249x; 1.0040x over previous
; #define LAS __attribute__((address_space(3)))
; __device__ __forceinline__ void spatial_phase(LAS unsigned char* lds, const float* w_s, const float* b_s, const float* normg, const float* ssq, const bf16_t* GVT, bf16_t* U) {
;     const int tid = tid_fresh(), lane = tid & 63, wid = tid >> 6, r32 = lane & 31, hi = lane >> 5;
;     for (int unit = blockIdx.x; unit < 528 * 8; unit += gridDim.x) {
;         const int c = unit >> 3, g = unit & 7;
;         const int i_st = tid & 127, cgp = tid >> 7;
;         float sp = 0.f;
;         { const int tk = tid & 127, pg = tid >> 7;
; #pragma unroll
;             for (int p = 0; p < 4; ++p) sp += ssq[(size_t)(pg * 4 + p) * MALL + c * 128 + tk]; }
;         f32x4 wa[4], wb[4];
;         { const float* wrow = w_s + ((size_t)g * 128 + i_st) * 128 + 32 * cgp;
; #pragma unroll
;             for (int q = 0; q < 4; ++q) { wa[q] = *(const f32x4*)(wrow + 8 * q); wb[q] = *(const f32x4*)(wrow + 8 * q + 4); } }
;         bf16x8 bfr[8];
;         { const bf16_t* gp = GVT + ((size_t)c * GMW + g * 256 + 32 * wid + r32) * 128 + 8 * hi;
; #pragma unroll
;             for (int kk = 0; kk < 8; ++kk) bfr[kk] = *(const bf16x8*)(gp + 16 * kk); }
;         u32x2 uu[4][4]; float bsv[4];
; #pragma unroll
;         for (int ib = 0; ib < 4; ++ib) { const int i = 32 * ib + r32; bsv[ib] = b_s[g * 128 + i]; const bf16_t* up = U + (size_t)(c * 128 + i) * GMW + g * 256 + 32 * wid + 4 * hi;
; #pragma unroll
;             for (int q4 = 0; q4 < 4; ++q4) uu[ib][q4] = *(const u32x2*)(up + 8 * q4); }
;         f32x4 ng[4];
; #pragma unroll
;         for (int q4 = 0; q4 < 4; ++q4) ng[q4] = *(const f32x4*)(normg + g * 256 + 32 * wid + 4 * hi + 8 * q4);
;         { LAS float* red = (LAS float*)(lds + 32768); LAS float* rs = red + 512;
;             red[(tid >> 7) * 128 + (tid & 127)] = sp;
;             __syncthreads();
;             if (tid < 128) rs[tid] = rsqrtf(((red[tid] + red[128 + tid]) + (red[256 + tid] + red[384 + tid])) * (1.0f / GMW) + EPS);
;             __syncthreads();
; #pragma unroll
;             for (int q = 0; q < 4; ++q) { const f32x4 sa = *(const LAS f32x4*)(rs + 32 * cgp + 8 * q), sb = *(const LAS f32x4*)(rs + 32 * cgp + 8 * q + 4);
;                 const f32x4 pa = wa[q] * sa, pb = wb[q] * sb; u32x4 o; o.x = cvt_pk_bf16(pa[0], pa[1]); o.y = cvt_pk_bf16(pa[2], pa[3]); o.z = cvt_pk_bf16(pb[0], pb[1]); o.w = cvt_pk_bf16(pb[2], pb[3]);
.LBB0_203:
	s_or_b64 exec, exec, s[2:3]
	s_waitcnt lgkmcnt(0)
	v_mov_b32_e32 v0, v204
	s_cmpk_gt_i32 s86, 0x107f
	s_barrier
	s_cbranch_scc1 .LBB0_208
	s_load_dwordx4 s[24:27], s[84:85], 0x38
	s_load_dwordx2 s[2:3], s[84:85], 0x48
	v_ashrrev_i32_e32 v11, 7, v0
	v_lshlrev_b32_e32 v6, 5, v11
	v_ashrrev_i32_e32 v7, 31, v6
	s_waitcnt lgkmcnt(0)
	v_mov_b32_e32 v4, s26
	v_mov_b32_e32 v5, s27
	v_lshl_add_u64 v[84:85], v[6:7], 2, v[4:5]
	v_ashrrev_i32_e32 v4, 1, v0
	v_and_b32_e32 v4, 0xffffffe0, v4
	v_mov_b32_e32 v2, s24
	v_mov_b32_e32 v3, s25
	v_and_b32_e32 v140, 31, v0
	v_lshlrev_b32_e32 v12, 2, v11
	v_ashrrev_i32_e32 v5, 31, v4
	v_bfe_u32 v1, v0, 5, 1
	v_and_b32_e32 v10, 0x7f, v0
	v_mov_b32_e32 v81, 0
	v_or_b32_e32 v86, v4, v140
	v_lshl_add_u64 v[8:9], v[4:5], 1, s[64:65]
	v_lshl_add_u64 v[2:3], v[4:5], 2, v[2:3]
	s_movk_i32 s6, 0x80
	s_mov_b32 s8, 0x42000
	v_or_b32_e32 v4, 1, v12
	v_lshlrev_b32_e32 v80, 2, v10
	v_lshlrev_b32_e32 v6, 4, v1
	v_mov_b32_e32 v7, v81
	v_lshl_add_u32 v141, v0, 2, 0
	v_cmp_gt_i32_e32 vcc, s6, v0
	v_and_b32_e32 v0, 0xffffff80, v0
	v_mad_i64_i32 v[96:97], s[6:7], v4, s8, 0
	v_or_b32_e32 v4, 2, v12
	v_lshl_add_u64 v[82:83], s[12:13], 0, v[80:81]
	v_lshlrev_b32_e32 v13, 7, v10
	v_lshlrev_b32_e32 v80, 3, v1
	v_lshl_add_u64 v[92:93], v[2:3], 0, v[6:7]
	v_add_u32_e32 v142, 0, v0
	v_lshl_add_u32 v0, v11, 13, 0
	v_lshlrev_b32_e32 v2, 4, v10
	v_lshl_add_u32 v1, v1, 11, 0
	v_lshlrev_b32_e32 v3, 4, v140
	v_mad_i64_i32 v[98:99], s[6:7], v4, s8, 0
	v_or_b32_e32 v4, 3, v12
	v_mov_b32_e32 v87, v5
	v_lshl_add_u64 v[88:89], s[10:11], 0, v[6:7]
	v_lshl_add_u64 v[90:91], v[8:9], 0, v[80:81]
	s_mov_b32 s9, 0
	v_mad_i64_i32 v[94:95], s[6:7], v12, s8, 0
	v_mad_i64_i32 v[100:101], s[6:7], v4, s8, 0
	v_or_b32_e32 v143, 32, v140
	v_or_b32_e32 v144, 64, v140
	v_or_b32_e32 v145, 0x60, v140
	v_lshlrev_b32_e32 v146, 2, v13
	v_mov_b32_e32 v147, 0x358637bd
	s_mov_b32 s12, 0x800000
	v_add_u32_e32 v148, v0, v2
	v_add_u32_e32 v149, v1, v3
	s_mov_b32 s13, s86
	s_and_b32 s11, s13, 7
	v_lshl_or_b32 v162, s11, 16, v146
	v_mov_b32_e32 v163, v81
	v_lshl_add_u64 v[162:163], v[84:85], 0, v[162:163]
	global_load_dwordx4 v[164:167], v[162:163], off offset:48
	global_load_dwordx4 v[168:171], v[162:163], off offset:32
	global_load_dwordx4 v[172:175], v[162:163], off offset:16
	global_load_dwordx4 v[184:187], v[162:163], off
	global_load_dwordx4 v[188:191], v[162:163], off offset:112
	global_load_dwordx4 v[196:199], v[162:163], off offset:96
	global_load_dwordx4 v[200:203], v[162:163], off offset:80
	global_load_dwordx4 v[244:247], v[162:163], off offset:64
	s_branch .LBB0_206
.LBB0_205:
	s_or_b64 exec, exec, s[10:11]
	s_waitcnt lgkmcnt(0)
	s_barrier
	ds_read_b128 v[152:155], v142 offset:34816
	ds_read_b128 v[156:159], v142 offset:34832
	s_add_i32 s13, s13, s50
	s_cmpk_lt_i32 s13, 0x1080
	s_waitcnt vmcnt(24) lgkmcnt(1)
	v_pk_mul_f32 v[76:77], v[184:185], v[152:153]
	s_waitcnt lgkmcnt(0)
	v_pk_mul_f32 v[152:153], v[174:175], v[158:159]
	v_pk_mul_f32 v[74:75], v[172:173], v[156:157]
	v_pk_mul_f32 v[78:79], v[186:187], v[154:155]
	v_cvt_pk_bf16_f32 v72, v76, v77
	s_nop 0
	v_cvt_pk_bf16_f32 v73, v78, v79
	v_cvt_pk_bf16_f32 v74, v74, v75
	v_cvt_pk_bf16_f32 v75, v152, v153
	ds_write_b128 v148, v[72:75]
	ds_read_b128 v[72:75], v142 offset:34848
	ds_read_b128 v[76:79], v142 offset:34864
	s_waitcnt lgkmcnt(1)
	v_pk_mul_f32 v[68:69], v[168:169], v[72:73]
	s_waitcnt lgkmcnt(0)
	v_pk_mul_f32 v[72:73], v[166:167], v[78:79]
	v_pk_mul_f32 v[66:67], v[164:165], v[76:77]
	v_pk_mul_f32 v[70:71], v[170:171], v[74:75]
	v_cvt_pk_bf16_f32 v64, v68, v69
	s_waitcnt vmcnt(15)
	s_waitcnt vmcnt(15)
	v_permlane32_swap_b32 v136, v138
	v_permlane32_swap_b32 v137, v139
	v_lshlrev_b32_e32 v74, 16, v139
	v_cvt_pk_bf16_f32 v65, v70, v71
	v_cvt_pk_bf16_f32 v66, v66, v67
	v_cvt_pk_bf16_f32 v67, v72, v73
	ds_write_b128 v148, v[64:67] offset:2048
	ds_read_b128 v[64:67], v142 offset:34880
	ds_read_b128 v[68:71], v142 offset:34896
	v_lshlrev_b32_e32 v72, 16, v138
	v_and_b32_e32 v73, 0xffff0000, v138
	v_and_b32_e32 v75, 0xffff0000, v139
	s_waitcnt lgkmcnt(1)
	v_pk_mul_f32 v[12:13], v[244:245], v[64:65]
	s_waitcnt lgkmcnt(0)
	v_pk_mul_f32 v[64:65], v[202:203], v[70:71]
	v_pk_mul_f32 v[10:11], v[200:201], v[68:69]
	v_pk_mul_f32 v[14:15], v[246:247], v[66:67]
	v_cvt_pk_bf16_f32 v8, v12, v13
	s_waitcnt vmcnt(14)
	s_waitcnt vmcnt(14)
	v_permlane32_swap_b32 v132, v134
	v_permlane32_swap_b32 v133, v135
	v_lshlrev_b32_e32 v76, 16, v134
	v_cvt_pk_bf16_f32 v9, v14, v15
	v_cvt_pk_bf16_f32 v10, v10, v11
	v_cvt_pk_bf16_f32 v11, v64, v65
	ds_write_b128 v148, v[8:11] offset:4096
	ds_read_b128 v[8:11], v142 offset:34912
	ds_read_b128 v[12:15], v142 offset:34928
	v_and_b32_e32 v77, 0xffff0000, v134
	v_lshlrev_b32_e32 v78, 16, v135
	s_waitcnt vmcnt(13)
	s_waitcnt vmcnt(13)
	v_permlane32_swap_b32 v128, v130
	v_permlane32_swap_b32 v129, v131
	v_and_b32_e32 v79, 0xffff0000, v131
	s_waitcnt lgkmcnt(1)
	v_pk_mul_f32 v[4:5], v[196:197], v[8:9]
	s_waitcnt lgkmcnt(0)
	v_pk_mul_f32 v[8:9], v[190:191], v[14:15]
	v_pk_mul_f32 v[2:3], v[188:189], v[12:13]
	v_pk_mul_f32 v[6:7], v[198:199], v[10:11]
	v_cvt_pk_bf16_f32 v0, v4, v5
	s_nop 0
	v_cvt_pk_bf16_f32 v1, v6, v7
	v_cvt_pk_bf16_f32 v2, v2, v3
	v_cvt_pk_bf16_f32 v3, v8, v9
	ds_write_b128 v148, v[0:3] offset:6144
	s_waitcnt lgkmcnt(0)
	s_barrier
; __device__ __forceinline__ unsigned cvt_pk_bf16(float lo, float hi) { unsigned r; asm volatile("v_cvt_pk_bf16_f32 %0, %1, %2" : "=v"(r) : "v"(lo), "v"(hi)); return r; }
; #define LAS __attribute__((address_space(3)))
; __device__ __forceinline__ float bflo(unsigned w) { return __uint_as_float(w << 16); }
; __device__ __forceinline__ float bfhi(unsigned w) { return __uint_as_float(w & 0xffff0000u); }
; __device__ __forceinline__ void spatial_phase(LAS unsigned char* lds, const float* w_s, const float* b_s, const float* normg, const float* ssq, const bf16_t* GVT, bf16_t* U) {
;     ...
;         for (int ib = 0; ib < 4; ++ib) {
;             f32x16 acc = {};
; #pragma unroll
;             for (int kk = 0; kk < 8; ++kk) { const bf16x8 af = *(const LAS bf16x8*)(lds + (2 * kk + hi) * 2048 + (32 * ib + r32) * 16);
;                 acc = __builtin_amdgcn_mfma_f32_32x32x16_bf16(bfr[kk], af, acc, 0, 0, 0); }
;             const int i = 32 * ib + r32; bf16_t* up = U + (size_t)(c * 128 + i) * GMW + g * 256 + 32 * wid + 4 * hi;
; #pragma unroll
;             for (int q4 = 0; q4 < 4; ++q4) { const u32x2 u2 = uu[ib][q4]; const float bb = bsv[ib];
;                 const float o0 = bflo(u2.x) * (acc[4 * q4 + 0] * ng[q4][0] + bb), o1 = bfhi(u2.x) * (acc[4 * q4 + 1] * ng[q4][1] + bb), o2 = bflo(u2.y) * (acc[4 * q4 + 2] * ng[q4][2] + bb), o3 = bfhi(u2.y) * (acc[4 * q4 + 3] * ng[q4][3] + bb);
;                 u32x2 w; w.x = cvt_pk_bf16(o0, o1); w.y = cvt_pk_bf16(o2, o3); *(u32x2*)(up + 8 * q4) = w; }
	ds_read_b128 v[0:3], v149
	ds_read_b128 v[64:67], v149 offset:4096
	s_waitcnt lgkmcnt(1)
	v_mfma_f32_32x32x16_bf16 v[0:15], v[56:59], v[0:3], 0
	s_waitcnt lgkmcnt(0)
	v_mfma_f32_32x32x16_bf16 v[0:15], v[52:55], v[64:67], v[0:15]
	ds_read_b128 v[64:67], v149 offset:8192
	ds_read_b128 v[68:71], v149 offset:12288
	s_waitcnt lgkmcnt(1)
	v_mfma_f32_32x32x16_bf16 v[0:15], v[48:51], v[64:67], v[0:15]
	s_waitcnt lgkmcnt(0)
	v_mfma_f32_32x32x16_bf16 v[0:15], v[44:47], v[68:71], v[0:15]
	ds_read_b128 v[64:67], v149 offset:16384
	ds_read_b128 v[68:71], v149 offset:20480
	s_waitcnt lgkmcnt(1)
	v_mfma_f32_32x32x16_bf16 v[0:15], v[40:43], v[64:67], v[0:15]
	ds_read_b128 v[64:67], v149 offset:24576
	s_waitcnt lgkmcnt(1)
	v_mfma_f32_32x32x16_bf16 v[0:15], v[36:39], v[68:71], v[0:15]
	ds_read_b128 v[68:71], v149 offset:28672
	s_waitcnt lgkmcnt(1)
	v_mfma_f32_32x32x16_bf16 v[0:15], v[24:27], v[64:67], v[0:15]
	v_lshlrev_b32_e32 v64, 16, v136
	v_and_b32_e32 v65, 0xffff0000, v136
	v_lshlrev_b32_e32 v66, 16, v137
	v_and_b32_e32 v67, 0xffff0000, v137
	s_waitcnt lgkmcnt(0)
	v_mfma_f32_32x32x16_bf16 v[0:15], v[16:19], v[68:71], v[0:15]
	s_waitcnt vmcnt(5)
	s_nop 10
	v_fma_f32 v0, v60, v0, v151
	v_fma_f32 v1, v61, v1, v151
	v_fma_f32 v2, v62, v2, v151
	v_fma_f32 v3, v63, v3, v151
	v_mul_f32_e32 v0, v0, v72
	v_mul_f32_e32 v1, v1, v73
	s_waitcnt vmcnt(4)
	v_fma_f32 v4, v32, v4, v151
	v_fma_f32 v5, v33, v5, v151
	v_fma_f32 v6, v34, v6, v151
	v_fma_f32 v7, v35, v7, v151
	v_mul_f32_e32 v2, v2, v74
	v_mul_f32_e32 v3, v3, v75
	v_cvt_pk_bf16_f32 v214, v0, v1
	v_cvt_pk_bf16_f32 v215, v2, v3
	v_mul_f32_e32 v4, v4, v64
	v_mul_f32_e32 v5, v5, v65
	v_mul_f32_e32 v6, v6, v66
	v_mul_f32_e32 v7, v7, v67
	v_cvt_pk_bf16_f32 v212, v4, v5
	v_cvt_pk_bf16_f32 v213, v6, v7
	s_nop 1
	v_permlane32_swap_b32 v212, v214
	v_permlane32_swap_b32 v213, v215
	v_lshl_add_u64 v[162:163], v[126:127], 0, v[160:161]
	global_store_dwordx4 v[162:163], v[212:215], off
	v_and_b32_e32 v0, 0xffff0000, v135
	s_waitcnt vmcnt(4)
	v_fma_f32 v1, v31, v11, v151
	v_fma_f32 v8, v28, v8, v151
	v_fma_f32 v9, v29, v9, v151
	v_fma_f32 v10, v30, v10, v151
	v_mul_f32_e32 v1, v1, v0
	v_mul_f32_e32 v8, v8, v76
	v_mul_f32_e32 v9, v9, v77
	v_mul_f32_e32 v10, v10, v78
	v_cvt_pk_bf16_f32 v218, v8, v9
	v_cvt_pk_bf16_f32 v219, v10, v1
	v_lshlrev_b32_e32 v0, 16, v132
	s_waitcnt vmcnt(3)
	v_fma_f32 v1, v20, v12, v151
	v_mul_f32_e32 v0, v1, v0
	v_and_b32_e32 v1, 0xffff0000, v132
	v_fma_f32 v2, v21, v13, v151
	v_mul_f32_e32 v1, v2, v1
	v_lshlrev_b32_e32 v2, 16, v133
	v_fma_f32 v3, v22, v14, v151
	v_mul_f32_e32 v2, v3, v2
	v_and_b32_e32 v3, 0xffff0000, v133
	v_fmac_f32_e32 v151, v23, v15
	v_mul_f32_e32 v3, v151, v3
	v_cvt_pk_bf16_f32 v216, v0, v1
	v_cvt_pk_bf16_f32 v217, v2, v3
	ds_read_b128 v[0:3], v149 offset:512
	ds_read_b128 v[64:67], v149 offset:4608
	s_waitcnt lgkmcnt(1)
	v_mfma_f32_32x32x16_bf16 v[0:15], v[56:59], v[0:3], 0
	v_or_b32_e32 v74, 32, v108
	v_lshlrev_b32_e32 v76, 16, v130
	v_and_b32_e32 v77, 0xffff0000, v130
	v_ashrrev_i32_e32 v75, 31, v74
	v_lshlrev_b32_e32 v78, 16, v131
	v_lshlrev_b32_e32 v130, 16, v128
	v_and_b32_e32 v128, 0xffff0000, v128
	s_waitcnt lgkmcnt(0)
	v_mfma_f32_32x32x16_bf16 v[0:15], v[52:55], v[64:67], v[0:15]
	ds_read_b128 v[64:67], v149 offset:8704
	ds_read_b128 v[68:71], v149 offset:12800
	s_waitcnt lgkmcnt(1)
	v_mfma_f32_32x32x16_bf16 v[0:15], v[48:51], v[64:67], v[0:15]
	s_waitcnt lgkmcnt(0)
	v_mfma_f32_32x32x16_bf16 v[0:15], v[44:47], v[68:71], v[0:15]
	ds_read_b128 v[64:67], v149 offset:16896
	ds_read_b128 v[68:71], v149 offset:20992
	s_nop 1
	v_permlane32_swap_b32 v216, v218
	v_permlane32_swap_b32 v217, v219
	v_lshl_add_u64 v[162:163], v[126:127], 0, v[160:161]
	global_store_dwordx4 v[162:163], v[216:219], off offset:32
	s_waitcnt lgkmcnt(1)
	v_mfma_f32_32x32x16_bf16 v[0:15], v[40:43], v[64:67], v[0:15]
	ds_read_b128 v[64:67], v149 offset:25088
	s_waitcnt lgkmcnt(1)
	v_mfma_f32_32x32x16_bf16 v[0:15], v[36:39], v[68:71], v[0:15]
	ds_read_b128 v[68:71], v149 offset:29184
	s_waitcnt lgkmcnt(1)
	v_mfma_f32_32x32x16_bf16 v[0:15], v[24:27], v[64:67], v[0:15]
	v_lshlrev_b64 v[64:65], 12, v[74:75]
	v_lshlrev_b32_e32 v66, 16, v129
	v_and_b32_e32 v67, 0xffff0000, v129
	v_lshl_add_u64 v[74:75], v[102:103], 0, v[64:65]
	s_waitcnt vmcnt(14)
	v_permlane32_swap_b32 v122, v124
	v_permlane32_swap_b32 v123, v125
	v_lshlrev_b32_e32 v129, 16, v124
	s_waitcnt lgkmcnt(0)
	v_mfma_f32_32x32x16_bf16 v[0:15], v[16:19], v[68:71], v[0:15]
	s_nop 11
	v_fma_f32 v0, v60, v0, v150
	v_fma_f32 v1, v61, v1, v150
	v_fma_f32 v2, v62, v2, v150
	v_fma_f32 v3, v63, v3, v150
	v_mul_f32_e32 v0, v0, v76
	v_mul_f32_e32 v1, v1, v77
	v_fma_f32 v4, v32, v4, v150
	v_fma_f32 v5, v33, v5, v150
	v_fma_f32 v6, v34, v6, v150
	v_fma_f32 v7, v35, v7, v150
	v_mul_f32_e32 v2, v2, v78
	v_mul_f32_e32 v3, v3, v79
	v_cvt_pk_bf16_f32 v222, v0, v1
	v_cvt_pk_bf16_f32 v223, v2, v3
	v_mul_f32_e32 v4, v4, v130
	v_mul_f32_e32 v5, v5, v128
	v_mul_f32_e32 v6, v6, v66
	v_mul_f32_e32 v7, v7, v67
	v_cvt_pk_bf16_f32 v220, v4, v5
	v_cvt_pk_bf16_f32 v221, v6, v7
	s_nop 1
	v_permlane32_swap_b32 v220, v222
	v_permlane32_swap_b32 v221, v223
	v_lshl_add_u64 v[162:163], v[74:75], 0, v[160:161]
	global_store_dwordx4 v[162:163], v[220:223], off
	v_and_b32_e32 v0, 0xffff0000, v124
	v_fma_f32 v1, v29, v9, v150
	v_mul_f32_e32 v0, v1, v0
	v_lshlrev_b32_e32 v1, 16, v125
	v_fma_f32 v2, v30, v10, v150
	v_fma_f32 v8, v28, v8, v150
	v_mul_f32_e32 v1, v2, v1
	v_and_b32_e32 v2, 0xffff0000, v125
	v_fma_f32 v3, v31, v11, v150
	v_mul_f32_e32 v8, v8, v129
	v_mul_f32_e32 v2, v3, v2
	v_cvt_pk_bf16_f32 v226, v8, v0
	v_cvt_pk_bf16_f32 v227, v1, v2
	v_lshlrev_b32_e32 v0, 16, v122
	v_fma_f32 v1, v20, v12, v150
	v_mul_f32_e32 v0, v1, v0
	v_and_b32_e32 v1, 0xffff0000, v122
	v_fma_f32 v2, v21, v13, v150
	v_mul_f32_e32 v1, v2, v1
	v_lshlrev_b32_e32 v2, 16, v123
	v_fma_f32 v3, v22, v14, v150
	v_mul_f32_e32 v2, v3, v2
	v_and_b32_e32 v3, 0xffff0000, v123
	v_fmac_f32_e32 v150, v23, v15
	v_mul_f32_e32 v3, v150, v3
	v_cvt_pk_bf16_f32 v224, v0, v1
	v_cvt_pk_bf16_f32 v225, v2, v3
	ds_read_b128 v[0:3], v149 offset:1024
	ds_read_b128 v[64:67], v149 offset:5120
	s_waitcnt lgkmcnt(1)
; __device__ __forceinline__ unsigned cvt_pk_bf16(float lo, float hi) { unsigned r; asm volatile("v_cvt_pk_bf16_f32 %0, %1, %2" : "=v"(r) : "v"(lo), "v"(hi)); return r; }
; #define LAS __attribute__((address_space(3)))
; __device__ __forceinline__ float bflo(unsigned w) { return __uint_as_float(w << 16); }
; __device__ __forceinline__ float bfhi(unsigned w) { return __uint_as_float(w & 0xffff0000u); }
; __device__ __forceinline__ void spatial_phase(LAS unsigned char* lds, const float* w_s, const float* b_s, const float* normg, const float* ssq, const bf16_t* GVT, bf16_t* U) {
;     ...
;         for (int ib = 0; ib < 4; ++ib) {
;             f32x16 acc = {};
; #pragma unroll
;             for (int kk = 0; kk < 8; ++kk) { const bf16x8 af = *(const LAS bf16x8*)(lds + (2 * kk + hi) * 2048 + (32 * ib + r32) * 16);
;                 acc = __builtin_amdgcn_mfma_f32_32x32x16_bf16(bfr[kk], af, acc, 0, 0, 0); }
;             const int i = 32 * ib + r32; bf16_t* up = U + (size_t)(c * 128 + i) * GMW + g * 256 + 32 * wid + 4 * hi;
; #pragma unroll
;             for (int q4 = 0; q4 < 4; ++q4) { const u32x2 u2 = uu[ib][q4]; const float bb = bsv[ib];
;                 const float o0 = bflo(u2.x) * (acc[4 * q4 + 0] * ng[q4][0] + bb), o1 = bfhi(u2.x) * (acc[4 * q4 + 1] * ng[q4][1] + bb), o2 = bflo(u2.y) * (acc[4 * q4 + 2] * ng[q4][2] + bb), o3 = bfhi(u2.y) * (acc[4 * q4 + 3] * ng[q4][3] + bb);
;                 u32x2 w; w.x = cvt_pk_bf16(o0, o1); w.y = cvt_pk_bf16(o2, o3); *(u32x2*)(up + 8 * q4) = w; }
;         }
;         __syncthreads();
	v_mfma_f32_32x32x16_bf16 v[0:15], v[56:59], v[0:3], 0
	v_or_b32_e32 v76, 64, v108
	s_waitcnt vmcnt(14)
	v_permlane32_swap_b32 v118, v120
	v_permlane32_swap_b32 v119, v121
	v_lshlrev_b32_e32 v78, 16, v120
	v_and_b32_e32 v79, 0xffff0000, v120
	v_ashrrev_i32_e32 v77, 31, v76
	v_lshlrev_b32_e32 v120, 16, v121
	v_and_b32_e32 v121, 0xffff0000, v121
	v_lshlrev_b32_e32 v122, 16, v118
	s_waitcnt lgkmcnt(0)
	v_mfma_f32_32x32x16_bf16 v[0:15], v[52:55], v[64:67], v[0:15]
	ds_read_b128 v[64:67], v149 offset:9216
	ds_read_b128 v[68:71], v149 offset:13312
	s_waitcnt lgkmcnt(1)
	v_mfma_f32_32x32x16_bf16 v[0:15], v[48:51], v[64:67], v[0:15]
	s_waitcnt lgkmcnt(0)
	v_mfma_f32_32x32x16_bf16 v[0:15], v[44:47], v[68:71], v[0:15]
	ds_read_b128 v[64:67], v149 offset:17408
	ds_read_b128 v[68:71], v149 offset:21504
	s_nop 1
	v_permlane32_swap_b32 v224, v226
	v_permlane32_swap_b32 v225, v227
	v_lshl_add_u64 v[162:163], v[74:75], 0, v[160:161]
	global_store_dwordx4 v[162:163], v[224:227], off offset:32
	s_waitcnt lgkmcnt(1)
	v_mfma_f32_32x32x16_bf16 v[0:15], v[40:43], v[64:67], v[0:15]
	ds_read_b128 v[64:67], v149 offset:25600
	s_waitcnt lgkmcnt(1)
	v_mfma_f32_32x32x16_bf16 v[0:15], v[36:39], v[68:71], v[0:15]
	ds_read_b128 v[68:71], v149 offset:29696
	s_waitcnt lgkmcnt(1)
	v_mfma_f32_32x32x16_bf16 v[0:15], v[24:27], v[64:67], v[0:15]
	v_lshlrev_b64 v[64:65], 12, v[76:77]
	v_and_b32_e32 v66, 0xffff0000, v118
	v_and_b32_e32 v118, 0xffff0000, v119
	v_lshl_add_u64 v[76:77], v[102:103], 0, v[64:65]
	v_lshlrev_b32_e32 v67, 16, v119
	s_waitcnt lgkmcnt(0)
	v_mfma_f32_32x32x16_bf16 v[0:15], v[16:19], v[68:71], v[0:15]
	s_nop 11
	v_fma_f32 v0, v60, v0, v109
	v_fma_f32 v1, v61, v1, v109
	v_fma_f32 v2, v62, v2, v109
	v_fma_f32 v3, v63, v3, v109
	v_mul_f32_e32 v0, v0, v78
	v_mul_f32_e32 v1, v1, v79
	v_fma_f32 v7, v35, v7, v109
	v_mul_f32_e32 v2, v2, v120
	v_mul_f32_e32 v3, v3, v121
	v_cvt_pk_bf16_f32 v230, v0, v1
	v_cvt_pk_bf16_f32 v231, v2, v3
	v_fma_f32 v4, v32, v4, v109
	v_fma_f32 v5, v33, v5, v109
	v_fma_f32 v6, v34, v6, v109
	v_mul_f32_e32 v1, v7, v118
	v_mul_f32_e32 v4, v4, v122
	v_mul_f32_e32 v5, v5, v66
	v_mul_f32_e32 v6, v6, v67
	v_cvt_pk_bf16_f32 v228, v4, v5
	v_cvt_pk_bf16_f32 v229, v6, v1
	s_nop 1
	v_permlane32_swap_b32 v228, v230
	v_permlane32_swap_b32 v229, v231
	v_lshl_add_u64 v[162:163], v[76:77], 0, v[160:161]
	global_store_dwordx4 v[162:163], v[228:231], off
	s_waitcnt vmcnt(15)
	v_permlane32_swap_b32 v114, v116
	v_permlane32_swap_b32 v115, v117
	v_lshlrev_b32_e32 v0, 16, v116
	v_fma_f32 v1, v28, v8, v109
	v_mul_f32_e32 v0, v1, v0
	v_and_b32_e32 v1, 0xffff0000, v116
	v_fma_f32 v2, v29, v9, v109
	v_mul_f32_e32 v1, v2, v1
	v_lshlrev_b32_e32 v2, 16, v117
	v_fma_f32 v3, v30, v10, v109
	v_mul_f32_e32 v2, v3, v2
	v_and_b32_e32 v3, 0xffff0000, v117
	v_fma_f32 v4, v31, v11, v109
	v_mul_f32_e32 v3, v4, v3
	v_cvt_pk_bf16_f32 v234, v0, v1
	v_cvt_pk_bf16_f32 v235, v2, v3
	v_lshlrev_b32_e32 v0, 16, v114
	v_fma_f32 v1, v20, v12, v109
	v_mul_f32_e32 v0, v1, v0
	v_and_b32_e32 v1, 0xffff0000, v114
	v_fma_f32 v2, v21, v13, v109
	v_mul_f32_e32 v1, v2, v1
	v_lshlrev_b32_e32 v2, 16, v115
	v_fma_f32 v3, v22, v14, v109
	v_mul_f32_e32 v2, v3, v2
	v_and_b32_e32 v3, 0xffff0000, v115
	v_fmac_f32_e32 v109, v23, v15
	v_mul_f32_e32 v3, v109, v3
	v_cvt_pk_bf16_f32 v232, v0, v1
	v_cvt_pk_bf16_f32 v233, v2, v3
	ds_read_b128 v[0:3], v149 offset:1536
	ds_read_b128 v[64:67], v149 offset:5632
	s_waitcnt lgkmcnt(1)
	v_mfma_f32_32x32x16_bf16 v[0:15], v[56:59], v[0:3], 0
	s_waitcnt lgkmcnt(0)
	v_mfma_f32_32x32x16_bf16 v[0:15], v[52:55], v[64:67], v[0:15]
	ds_read_b128 v[52:55], v149 offset:9728
	ds_read_b128 v[56:59], v149 offset:13824
	s_waitcnt lgkmcnt(1)
	v_mfma_f32_32x32x16_bf16 v[0:15], v[48:51], v[52:55], v[0:15]
	s_waitcnt lgkmcnt(0)
	v_mfma_f32_32x32x16_bf16 v[0:15], v[44:47], v[56:59], v[0:15]
	ds_read_b128 v[44:47], v149 offset:17920
	ds_read_b128 v[48:51], v149 offset:22016
	s_nop 1
	v_permlane32_swap_b32 v232, v234
	v_permlane32_swap_b32 v233, v235
	v_lshl_add_u64 v[162:163], v[76:77], 0, v[160:161]
	global_store_dwordx4 v[162:163], v[232:235], off offset:32
	s_waitcnt lgkmcnt(1)
	v_mfma_f32_32x32x16_bf16 v[0:15], v[40:43], v[44:47], v[0:15]
	ds_read_b128 v[40:43], v149 offset:30208
	v_or_b32_e32 v44, 0x60, v108
	s_waitcnt vmcnt(7)
	s_waitcnt vmcnt(7)
	v_permlane32_swap_b32 v110, v112
	v_permlane32_swap_b32 v111, v113
	v_lshlrev_b32_e32 v46, 16, v112
	v_and_b32_e32 v47, 0xffff0000, v112
	v_ashrrev_i32_e32 v45, 31, v44
	s_waitcnt lgkmcnt(1)
	v_mfma_f32_32x32x16_bf16 v[0:15], v[36:39], v[48:51], v[0:15]
	ds_read_b128 v[36:39], v149 offset:26112
	v_lshlrev_b32_e32 v48, 16, v113
	s_waitcnt lgkmcnt(0)
	v_mfma_f32_32x32x16_bf16 v[0:15], v[24:27], v[36:39], v[0:15]
	v_and_b32_e32 v26, 0xffff0000, v113
	v_lshlrev_b64 v[24:25], 12, v[44:45]
	v_lshl_add_u64 v[24:25], v[102:103], 0, v[24:25]
	s_waitcnt vmcnt(7)
	v_and_b32_e32 v36, 0xffff0000, v110
	v_lshlrev_b32_e32 v27, 16, v110
	v_mfma_f32_32x32x16_bf16 v[0:15], v[16:19], v[40:43], v[0:15]
	s_nop 11
	v_fma_f32 v0, v60, v0, v80
	v_fma_f32 v1, v61, v1, v80
	v_fma_f32 v2, v62, v2, v80
	v_fma_f32 v3, v63, v3, v80
	v_mul_f32_e32 v0, v0, v46
	v_mul_f32_e32 v1, v1, v47
	v_mul_f32_e32 v2, v2, v48
	v_mul_f32_e32 v3, v3, v26
	v_cvt_pk_bf16_f32 v238, v0, v1
	v_cvt_pk_bf16_f32 v239, v2, v3
	v_fma_f32 v5, v33, v5, v80
	v_lshlrev_b32_e32 v1, 16, v111
	v_fma_f32 v2, v34, v6, v80
	v_fma_f32 v4, v32, v4, v80
	v_mul_f32_e32 v0, v5, v36
	v_mul_f32_e32 v1, v2, v1
	v_and_b32_e32 v2, 0xffff0000, v111
	v_fma_f32 v3, v35, v7, v80
	v_mul_f32_e32 v4, v4, v27
	v_mul_f32_e32 v2, v3, v2
	v_cvt_pk_bf16_f32 v236, v4, v0
	v_cvt_pk_bf16_f32 v237, v1, v2
	s_nop 1
	v_permlane32_swap_b32 v236, v238
	v_permlane32_swap_b32 v237, v239
	v_lshl_add_u64 v[162:163], v[24:25], 0, v[160:161]
	global_store_dwordx4 v[162:163], v[236:239], off
	s_waitcnt vmcnt(7)
	s_waitcnt vmcnt(7)
	v_permlane32_swap_b32 v104, v106
	v_permlane32_swap_b32 v105, v107
	v_lshlrev_b32_e32 v0, 16, v106
	v_fma_f32 v1, v28, v8, v80
	v_mul_f32_e32 v0, v1, v0
	v_and_b32_e32 v1, 0xffff0000, v106
	v_fma_f32 v2, v29, v9, v80
	v_mul_f32_e32 v1, v2, v1
	v_lshlrev_b32_e32 v2, 16, v107
	v_fma_f32 v3, v30, v10, v80
	v_mul_f32_e32 v2, v3, v2
	v_and_b32_e32 v3, 0xffff0000, v107
	v_fma_f32 v4, v31, v11, v80
	v_mul_f32_e32 v3, v4, v3
	v_cvt_pk_bf16_f32 v242, v0, v1
	v_cvt_pk_bf16_f32 v243, v2, v3
	s_waitcnt vmcnt(7)
	v_lshlrev_b32_e32 v0, 16, v104
	v_fma_f32 v1, v20, v12, v80
	v_mul_f32_e32 v0, v1, v0
	v_and_b32_e32 v1, 0xffff0000, v104
	v_fma_f32 v2, v21, v13, v80
	v_mul_f32_e32 v1, v2, v1
	v_lshlrev_b32_e32 v2, 16, v105
	v_fma_f32 v3, v22, v14, v80
	v_mul_f32_e32 v2, v3, v2
	v_and_b32_e32 v3, 0xffff0000, v105
	v_fmac_f32_e32 v80, v23, v15
	v_mul_f32_e32 v3, v80, v3
	v_cvt_pk_bf16_f32 v240, v0, v1
	v_cvt_pk_bf16_f32 v241, v2, v3
	s_nop 1
	v_permlane32_swap_b32 v240, v242
	v_permlane32_swap_b32 v241, v243
	v_lshl_add_u64 v[162:163], v[24:25], 0, v[160:161]
	global_store_dwordx4 v[162:163], v[240:243], off offset:32
	s_barrier
	s_cbranch_scc0 .LBB0_208
; #define LAS __attribute__((address_space(3)))
; __device__ __forceinline__ void spatial_phase(LAS unsigned char* lds, const float* w_s, const float* b_s, const float* normg, const float* ssq, const bf16_t* GVT, bf16_t* U) {
;     ...
;     for (int unit = blockIdx.x; unit < 528 * 8; unit += gridDim.x) {
;         const int c = unit >> 3, g = unit & 7;
;         const int i_st = tid & 127, cgp = tid >> 7;
;         float sp = 0.f;
;         { const int tk = tid & 127, pg = tid >> 7;
; #pragma unroll
;             for (int p = 0; p < 4; ++p) sp += ssq[(size_t)(pg * 4 + p) * MALL + c * 128 + tk]; }
;         f32x4 wa[4], wb[4];
;         { const float* wrow = w_s + ((size_t)g * 128 + i_st) * 128 + 32 * cgp;
; #pragma unroll
;             for (int q = 0; q < 4; ++q) { wa[q] = *(const f32x4*)(wrow + 8 * q); wb[q] = *(const f32x4*)(wrow + 8 * q + 4); } }
;         bf16x8 bfr[8];
;         { const bf16_t* gp = GVT + ((size_t)c * GMW + g * 256 + 32 * wid + r32) * 128 + 8 * hi;
; #pragma unroll
;             for (int kk = 0; kk < 8; ++kk) bfr[kk] = *(const bf16x8*)(gp + 16 * kk); }
;         u32x2 uu[4][4]; float bsv[4];
; #pragma unroll
;         for (int ib = 0; ib < 4; ++ib) { const int i = 32 * ib + r32; bsv[ib] = b_s[g * 128 + i]; const bf16_t* up = U + (size_t)(c * 128 + i) * GMW + g * 256 + 32 * wid + 4 * hi;
; #pragma unroll
;             for (int q4 = 0; q4 < 4; ++q4) uu[ib][q4] = *(const u32x2*)(up + 8 * q4); }
;         f32x4 ng[4];
; #pragma unroll
;         for (int q4 = 0; q4 < 4; ++q4) ng[q4] = *(const f32x4*)(normg + g * 256 + 32 * wid + 4 * hi + 8 * q4);
;         { LAS float* red = (LAS float*)(lds + 32768); LAS float* rs = red + 512;
;             red[(tid >> 7) * 128 + (tid & 127)] = sp;
;             __syncthreads();
;             if (tid < 128) rs[tid] = rsqrtf(((red[tid] + red[128 + tid]) + (red[256 + tid] + red[384 + tid])) * (1.0f / GMW) + EPS);
;             __syncthreads();
.LBB0_206:
	v_mbcnt_lo_u32_b32 v160, -1, 0
	v_mbcnt_hi_u32_b32 v160, -1, v160
	v_lshrrev_b32_e32 v160, 5, v160
	v_sub_u32_e32 v161, 0, v160
	v_mul_u32_u24_e32 v160, 24, v160
	v_sub_u32_e32 v160, 16, v160
	s_ashr_i32 s6, s13, 3
	s_lshl_b32 s10, s6, 7
	s_ashr_i32 s11, s10, 31
	v_lshl_add_u64 v[0:1], s[10:11], 2, v[82:83]
	s_and_b32 s11, s13, 7
	s_lshl_b32 s8, s11, 8
	v_or_b32_e32 v108, s10, v140
	v_lshl_add_u64 v[16:17], v[86:87], 0, s[8:9]
	s_lshl_b32 s8, s11, 9
	v_ashrrev_i32_e32 v109, 31, v108
	v_lshl_add_u64 v[102:103], v[90:91], 0, s[8:9]
	v_lshlrev_b64 v[20:21], 12, v[108:109]
	s_ashr_i32 s7, s6, 31
	v_lshl_add_u64 v[126:127], v[102:103], 0, v[20:21]
	v_or_b32_e32 v20, s10, v143
	s_lshl_b64 s[6:7], s[6:7], 19
	v_ashrrev_i32_e32 v21, 31, v20
	v_lshl_or_b32 v80, s11, 16, v146
	v_lshlrev_b64 v[16:17], 8, v[16:17]
	v_lshl_add_u64 v[18:19], v[88:89], 0, s[6:7]
	v_lshlrev_b64 v[20:21], 12, v[20:21]
	v_lshl_add_u64 v[2:3], v[0:1], 0, v[94:95]
	v_lshl_add_u64 v[4:5], v[0:1], 0, v[96:97]
	v_lshl_add_u64 v[6:7], v[0:1], 0, v[98:99]
	v_lshl_add_u64 v[0:1], v[0:1], 0, v[100:101]
	v_lshl_add_u64 v[12:13], v[84:85], 0, v[80:81]
	v_lshl_add_u64 v[16:17], v[18:19], 0, v[16:17]
	v_lshl_add_u64 v[20:21], v[102:103], 0, v[20:21]
	global_load_dword v152, v[2:3], off
	global_load_dword v153, v[4:5], off
	global_load_dword v154, v[6:7], off
	global_load_dword v155, v[0:1], off
	s_nop 0
	s_nop 0
	s_nop 0
	global_load_dwordx4 v[56:59], v[16:17], off
	global_load_dwordx4 v[52:55], v[16:17], off offset:32
	global_load_dwordx4 v[48:51], v[16:17], off offset:64
	global_load_dwordx4 v[44:47], v[16:17], off offset:96
	global_load_dwordx4 v[40:43], v[16:17], off offset:128
	global_load_dwordx4 v[36:39], v[16:17], off offset:160
	global_load_dwordx4 v[24:27], v[16:17], off offset:192
	s_nop 0
	global_load_dwordx4 v[16:19], v[16:17], off offset:224
	s_nop 0
	v_lshl_add_u64 v[162:163], v[126:127], 0, v[160:161]
	global_load_dwordx4 v[136:139], v[162:163], off
	global_load_dwordx4 v[132:135], v[162:163], off offset:32
	v_lshl_add_u64 v[162:163], v[20:21], 0, v[160:161]
	global_load_dwordx4 v[128:131], v[162:163], off
	global_load_dwordx4 v[122:125], v[162:163], off offset:32
	v_or_b32_e32 v20, s10, v144
	v_ashrrev_i32_e32 v21, 31, v20
	v_lshlrev_b64 v[20:21], 12, v[20:21]
	v_lshl_add_u64 v[20:21], v[102:103], 0, v[20:21]
	v_lshl_or_b32 v22, v140, 2, s8
	v_lshl_add_u64 v[162:163], v[20:21], 0, v[160:161]
	global_load_dwordx4 v[118:121], v[162:163], off
	global_load_dwordx4 v[114:117], v[162:163], off offset:32
	global_load_dword v151, v22, s[2:3]
	global_load_dword v150, v22, s[2:3] offset:128
	global_load_dword v109, v22, s[2:3] offset:256
	global_load_dword v80, v22, s[2:3] offset:384
	v_or_b32_e32 v20, s10, v145
	v_ashrrev_i32_e32 v21, 31, v20
	v_lshlrev_b64 v[20:21], 12, v[20:21]
	s_lshl_b32 s8, s11, 10
	v_lshl_add_u64 v[104:105], v[102:103], 0, v[20:21]
	v_lshl_add_u64 v[20:21], v[92:93], 0, s[8:9]
	global_load_dwordx4 v[60:63], v[20:21], off
	global_load_dwordx4 v[32:35], v[20:21], off offset:32
	global_load_dwordx4 v[28:31], v[20:21], off offset:64
	s_nop 0
	global_load_dwordx4 v[20:23], v[20:21], off offset:96
	s_nop 0
	v_lshl_add_u64 v[162:163], v[104:105], 0, v[160:161]
	global_load_dwordx4 v[110:113], v[162:163], off
	global_load_dwordx4 v[104:107], v[162:163], off offset:32
	s_nop 0
	s_waitcnt vmcnt(27)
	v_add_f32_e32 v152, 0, v152
	s_waitcnt vmcnt(26)
	v_add_f32_e32 v152, v152, v153
	s_waitcnt vmcnt(25)
	v_add_f32_e32 v152, v152, v154
	s_waitcnt vmcnt(24)
	v_add_f32_e32 v152, v152, v155
	ds_write_b32 v141, v152 offset:32768
	s_waitcnt lgkmcnt(0)
	s_barrier
	s_and_saveexec_b64 s[10:11], vcc
	s_cbranch_execz .LBB0_205
	ds_read2st64_b32 v[152:153], v141 offset0:128 offset1:130
	ds_read2st64_b32 v[154:155], v141 offset0:132 offset1:134
	s_waitcnt lgkmcnt(1)
	v_mov_b32_e32 v156, v152
	s_waitcnt lgkmcnt(0)
	v_mov_b32_e32 v157, v154
	v_mov_b32_e32 v154, v153
	v_pk_add_f32 v[152:153], v[156:157], v[154:155]
	s_nop 0
	v_add_f32_e32 v152, v152, v153
	v_fmamk_f32 v152, v152, 0x3a000000, v147
	v_mul_f32_e32 v153, 0x4b800000, v152
	v_cmp_gt_f32_e64 s[6:7], s12, v152
	s_nop 1
	v_cndmask_b32_e64 v152, v152, v153, s[6:7]
	v_rsq_f32_e32 v152, v152
	s_nop 0
	v_mul_f32_e32 v153, 0x45800000, v152
	v_cndmask_b32_e64 v152, v152, v153, s[6:7]
	ds_write_b32 v141, v152 offset:34816
	s_branch .LBB0_205
